# sliding-window mixer bias table extended (as before) with the following code kept at its previous addresses
# speedup vs baseline: 1.0067x; 1.0067x over previous
; template <int MODE>
; __device__ __forceinline__ void attn_wave(LAS unsigned char* lds, const bf16_t* qkv, bf16_t* Yout, const float* sinks, int wi) {
;     ...
;             const int dbase = q0 + QSTEP * qt + c - k0 - 4 * g;
;             if (MODE == MODE_A) {
;                 float mx = -1e30f;
; #pragma unroll
;                 for (int nt = 0; nt < 2; ++nt)
; #pragma unroll
;                     for (int j = 0; j < 4; ++j) { const int dist = dbase - (16 * nt + j); const bool valid = (unsigned)dist < 128u;
;                         const float bias2 = lutp[qt * HSTEP * 128 + (dist & 127)];
;                         const float lg = valid ? (s[nt][j] * C1 + bias2) : -1e30f; s[nt][j] = lg; mx = fmaxf(mx, lg); }
.LBB0_315:
	s_waitcnt vmcnt(3)
	v_mfma_f32_16x16x32_bf16 v[120:123], v[120:123], v[96:99], 0
	s_waitcnt vmcnt(2)
	v_mfma_f32_16x16x32_bf16 v[124:127], v[124:127], v[100:103], v[120:123]
	s_waitcnt vmcnt(1)
	v_mfma_f32_16x16x32_bf16 v[120:123], v[132:135], v[96:99], 0
	s_waitcnt vmcnt(0)
	v_mfma_f32_16x16x32_bf16 v[120:123], v[128:131], v[100:103], v[120:123]
	v_lshlrev_b32_e32 v236, 2, v170
	v_lshl_add_u32 v236, s19, 1, v236
	v_add_u32_e32 v236, 0x140b0, v236
	ds_read_b32 v228, v236 offset:3148
	ds_read_b32 v229, v236 offset:3144
	ds_read_b32 v230, v236 offset:3140
	ds_read_b32 v231, v236 offset:3136
	ds_read_b32 v232, v236 offset:3084
	ds_read_b32 v233, v236 offset:3080
	ds_read_b32 v234, v236 offset:3076
	ds_read_b32 v235, v236 offset:3072
	v_mov_b32_e32 v237, 0x3e38aa3b
	s_waitcnt lgkmcnt(0)
	v_fma_f32 v133, v124, v237, v228
	v_fma_f32 v132, v125, v237, v229
	v_fma_f32 v125, v126, v237, v230
	v_fma_f32 v124, v127, v237, v231
	v_fma_f32 v127, v120, v237, v232
	v_fma_f32 v126, v121, v237, v233
	v_fma_f32 v121, v122, v237, v234
	v_fma_f32 v120, v123, v237, v235
	s_branch .LBB0_258
	s_nop 0
	s_nop 0
	s_nop 0
	s_nop 0
	s_nop 0
	s_nop 0
	s_nop 0
	s_nop 0
	s_nop 0
	s_nop 0
	s_nop 0
	s_nop 0
	s_nop 0
	s_nop 0
	s_nop 0
	s_nop 0
	s_nop 0
	s_nop 0
	s_nop 0
	s_nop 0
	s_nop 0
	s_nop 0
	s_nop 0
	s_nop 0
	s_nop 0
	s_nop 0
	s_nop 0
	s_nop 0
	s_nop 0
	s_nop 0
	s_nop 0
	s_nop 0
	s_nop 0
	s_nop 0
	s_nop 0
	s_nop 0
	s_nop 0
	s_nop 0
	s_nop 0
	s_nop 0
	s_nop 0
	s_nop 0
	s_nop 0
	s_nop 0
	s_nop 0
	s_nop 0
	s_nop 0
	s_nop 0
	s_nop 0
	s_nop 0
	s_nop 0
	s_nop 0
	s_nop 0
	s_nop 0
	s_nop 0
	s_nop 0
	s_nop 0
	s_nop 0
	s_nop 0
	s_nop 0
	s_nop 0
	s_nop 0
	s_nop 0
	s_nop 0
	s_nop 0
	s_nop 0
	s_nop 0
	s_nop 0
	s_nop 0
	s_nop 0
	s_nop 0
	s_nop 0
	s_nop 0
	s_nop 0
	s_nop 0
	s_nop 0
	s_nop 0
	s_nop 0
	s_nop 0
	s_nop 0
	s_nop 0
	s_nop 0
	s_nop 0
	s_nop 0
	s_nop 0
	s_nop 0
	s_nop 0
	s_nop 0
	s_nop 0
	s_nop 0
	s_nop 0
	s_nop 0
	s_nop 0
	s_nop 0
	s_nop 0
	s_nop 0
	s_nop 0
	s_nop 0
	s_nop 0
	s_nop 0
	s_nop 0
	s_nop 0
	s_nop 0
	s_nop 0
	s_nop 0
	s_nop 0
	s_nop 0
	s_nop 0
	s_nop 0
	s_nop 0
	s_nop 0
	s_nop 0
	s_nop 0
	s_nop 0
	s_nop 0
	s_nop 0
	s_nop 0
	s_nop 0
	s_nop 0
	s_nop 0
	s_nop 0
	s_nop 0
	s_nop 0
	s_nop 0
	s_nop 0
	s_nop 0
	s_nop 0
	s_nop 0
	s_nop 0
	s_nop 0
	s_nop 0
	s_nop 0
	s_nop 0
	s_nop 0
	s_nop 0
	s_nop 0
	s_nop 0
	s_nop 0
	s_nop 0
	s_nop 0
	s_nop 0
	s_nop 0
	s_nop 0
	s_nop 0
	s_nop 0
	s_nop 0
	s_nop 0
	s_nop 0
	s_nop 0
	s_nop 0
	s_nop 0
	s_nop 0
	s_nop 0
	s_nop 0
	s_nop 0
	s_nop 0
	s_nop 0
	s_nop 0
	s_nop 0
	s_nop 0
	s_nop 0
	s_nop 0
	s_nop 0
	s_nop 0
	s_nop 0
	s_nop 0
	s_nop 0
	s_nop 0
	s_nop 0
	s_nop 0
	s_nop 0
	s_nop 0
	s_nop 0
	s_nop 0
	s_nop 0
	s_nop 0
	s_nop 0
	s_nop 0
	s_nop 0
	s_nop 0
	s_nop 0
	s_nop 0
